# GDN prep items remapped: a (batch,head) is prepared by blocks of the XCD that later scans it, low chunks last (L2-resident when the scan starts)
# baseline (speedup 1.0000x reference)
.LBB0_760:
	s_and_b32 s2, s13, 7
	s_lshr_b32 s4, s13, 8
	s_bfe_u32 s5, s13, 0x50003
	s_lshl_b32 s2, s2, 1
	s_and_b32 s8, s4, 1
	s_or_b32 s2, s2, s8
	s_lshr_b32 s4, s4, 1
	s_xor_b32 s4, s4, 1
	s_lshl_b32 s4, s4, 5
	s_or_b32 s4, s4, s5
	s_lshl_b32 s4, s4, 2
	s_lshr_b32 s5, s2, 2
	s_lshl_b32 s5, s5, 8
	s_and_b32 s2, s2, 3
	s_or_b32 s4, s4, s5
	s_or_b32 s101, s4, s2
	s_sub_i32 s98, s101, s13
	s_lshl_b32 s98, s98, 2
	s_ashr_i32 s99, s98, 31
	s_lshr_b32 s2, s101, 2
	s_and_b32 s37, s101, 3
	v_mov_b32_e32 v106, v228
	s_bfe_u32 s8, s101, 0x60002
	s_lshl_b32 s5, s2, 6
	s_lshl_b32 s4, s37, 7
	s_cmp_lg_u32 s8, 0
	v_ashrrev_i32_e32 v104, 3, v106
	s_cselect_b64 s[8:9], -1, 0
	v_cmp_lt_i32_e32 vcc, 2, v104
	s_waitcnt vmcnt(0)
	v_add_u32_e32 v0, -3, v104
	s_or_b64 vcc, s[8:9], vcc
	v_cndmask_b32_e32 v0, 0, v0, vcc
	v_cndmask_b32_e64 v44, 0, 1.0, vcc
	v_cmp_lt_i32_e32 vcc, 1, v104
	v_add_u32_e32 v4, -2, v104
	s_or_b64 vcc, s[8:9], vcc
	v_cndmask_b32_e32 v4, 0, v4, vcc
	v_cndmask_b32_e64 v42, 0, 1.0, vcc
	v_cmp_lt_i32_e32 vcc, 0, v104
	v_add_u32_e32 v8, -1, v104
	s_or_b64 vcc, s[8:9], vcc
	v_cndmask_b32_e32 v8, 0, v8, vcc
	v_cndmask_b32_e64 v40, 0, 1.0, vcc
	v_cmp_lt_i32_e32 vcc, -1, v104
	s_movk_i32 s2, 0x110
	s_or_b64 vcc, s[8:9], vcc
	v_and_b32_e32 v105, 7, v106
	v_mul_lo_u32 v109, v104, s2
	s_movk_i32 s2, 0x410
	v_cndmask_b32_e32 v14, 0, v104, vcc
	v_lshlrev_b32_e32 v108, 4, v105
	v_mul_lo_u32 v1, v104, s2
	v_add_u32_e32 v0, s5, v0
	v_mov_b64_e32 v[12:13], s[94:95]
	v_add_u32_e32 v4, s5, v4
	v_add_u32_e32 v8, s5, v8
	v_add_u32_e32 v14, s5, v14
	v_add_u32_e32 v107, 0, v1
	v_or_b32_e32 v39, s4, v108
	v_mad_i64_i32 v[0:1], s[38:39], v0, s66, v[12:13]
	v_mad_i64_i32 v[4:5], s[38:39], v4, s66, v[12:13]
	v_mad_i64_i32 v[8:9], s[38:39], v8, s66, v[12:13]
	v_mad_i64_i32 v[12:13], s[8:9], v14, s66, v[12:13]
	v_lshl_add_u64 v[46:47], v[0:1], 0, s[26:27]
	v_lshlrev_b32_e32 v16, 1, v39
	v_lshl_add_u64 v[48:49], v[4:5], 0, s[26:27]
	v_lshl_add_u64 v[50:51], v[8:9], 0, s[26:27]
	v_lshl_add_u64 v[52:53], v[12:13], 0, s[26:27]
	v_lshl_add_u64 v[0:1], v[46:47], 0, v[16:17]
	v_lshl_add_u64 v[4:5], v[48:49], 0, v[16:17]
	v_lshl_add_u64 v[8:9], v[50:51], 0, v[16:17]
	v_lshl_add_u64 v[12:13], v[52:53], 0, v[16:17]
	flat_load_dwordx4 v[30:33], v[0:1]
	s_nop 0
	flat_load_dwordx4 v[0:3], v[0:1] offset:16
	s_nop 0
	flat_load_dwordx4 v[26:29], v[4:5]
	s_nop 0
	flat_load_dwordx4 v[4:7], v[4:5] offset:16
	s_nop 0
	flat_load_dwordx4 v[22:25], v[8:9]
	s_nop 0
	flat_load_dwordx4 v[8:11], v[8:9] offset:16
	s_nop 0
	flat_load_dwordx4 v[18:21], v[12:13]
	s_nop 0
	flat_load_dwordx4 v[12:15], v[12:13] offset:16
	s_mov_b32 s8, 0
	s_ashr_i32 s9, s8, 31
	s_lshl_b64 s[8:9], s[8:9], 3
	s_add_u32 s8, s0, s8
	s_addc_u32 s9, s1, s9
	s_load_dwordx2 s[8:9], s[8:9], 0x90
	v_lshlrev_b32_e32 v41, 2, v39
	v_cndmask_b32_e64 v38, 0, 1.0, vcc
	v_and_b32_e32 v111, 64, v234
	v_or_b32_e32 v16, 0x400, v16
	s_waitcnt lgkmcnt(0)
	s_add_u32 s8, s8, s15
	s_addc_u32 s9, s9, s14
	global_load_dwordx4 v[34:37], v41, s[8:9] offset:48
	global_load_dwordx4 v[54:57], v41, s[8:9] offset:32
	global_load_dwordx4 v[58:61], v41, s[8:9] offset:16
	global_load_dwordx4 v[62:65], v41, s[8:9]
	s_mov_b32 s8, 0
	s_ashr_i32 s9, s8, 31
	s_lshl_b64 s[8:9], s[8:9], 3
	s_add_u32 s8, s0, s8
	s_addc_u32 s9, s1, s9
	s_load_dwordx2 s[8:9], s[8:9], 0x90
	v_lshl_add_u32 v110, v105, 6, v107
	s_waitcnt lgkmcnt(0)
	s_add_u32 s8, s8, s16
	s_addc_u32 s9, s9, s17
	s_waitcnt vmcnt(0)
	v_lshlrev_b32_e32 v43, 16, v30
	v_and_b32_e32 v30, 0xffff0000, v30
	v_lshlrev_b32_e32 v84, 16, v18
	v_and_b32_e32 v18, 0xffff0000, v18
	v_pk_mul_f32 v[58:59], v[44:45], v[58:59] op_sel_hi:[0,1]
	v_pk_mul_f32 v[62:63], v[44:45], v[62:63] op_sel_hi:[0,1]
	v_pk_mul_f32 v[64:65], v[44:45], v[64:65] op_sel_hi:[0,1]
	v_fma_f32 v82, v63, v30, 0
	v_lshlrev_b32_e32 v30, 16, v31
	v_fma_f32 v83, v62, v43, 0
	v_fma_f32 v81, v64, v30, 0
	v_and_b32_e32 v30, 0xffff0000, v31
	v_lshlrev_b32_e32 v43, 16, v32
	v_and_b32_e32 v32, 0xffff0000, v32
	v_fma_f32 v80, v65, v30, 0
	v_pk_mul_f32 v[30:31], v[44:45], v[60:61] op_sel_hi:[0,1]
	v_fma_f32 v78, v59, v32, 0
	v_lshlrev_b32_e32 v32, 16, v33
	v_fma_f32 v45, v30, v32, 0
	v_and_b32_e32 v30, 0xffff0000, v33
	v_fma_f32 v79, v58, v43, 0
	v_fma_f32 v43, v31, v30, 0
	v_pk_mul_f32 v[58:59], v[44:45], v[56:57] op_sel_hi:[0,1]
	v_pk_mul_f32 v[62:63], v[44:45], v[54:55] op_sel_hi:[0,1]
	v_pk_mul_f32 v[54:55], v[44:45], v[36:37] op_sel_hi:[0,1]
	v_pk_mul_f32 v[56:57], v[44:45], v[34:35] op_sel_hi:[0,1]
	global_load_dwordx4 v[30:33], v41, s[8:9] offset:48
	global_load_dwordx4 v[34:37], v41, s[8:9] offset:32
	global_load_dwordx4 v[64:67], v41, s[8:9] offset:16
	global_load_dwordx4 v[68:71], v41, s[8:9]
	s_mov_b32 s8, 0
	s_ashr_i32 s9, s8, 31
	s_lshl_b64 s[8:9], s[8:9], 3
	s_add_u32 s8, s0, s8
	s_addc_u32 s9, s1, s9
	s_load_dwordx2 s[8:9], s[8:9], 0x90
	s_waitcnt lgkmcnt(0)
	s_add_u32 s8, s8, s18
	s_addc_u32 s9, s9, s19
	s_waitcnt vmcnt(0)
	v_pk_mul_f32 v[60:61], v[42:43], v[70:71] op_sel_hi:[0,1]
	v_pk_mul_f32 v[68:69], v[42:43], v[68:69] op_sel_hi:[0,1]
	v_lshlrev_b32_e32 v70, 16, v26
	v_and_b32_e32 v26, 0xffff0000, v26
	v_fmac_f32_e32 v82, v69, v26
	v_lshlrev_b32_e32 v26, 16, v27
	v_fmac_f32_e32 v81, v60, v26
	v_and_b32_e32 v26, 0xffff0000, v27
	v_fmac_f32_e32 v80, v61, v26
	v_pk_mul_f32 v[60:61], v[42:43], v[64:65] op_sel_hi:[0,1]
	v_lshlrev_b32_e32 v64, 16, v28
	v_and_b32_e32 v28, 0xffff0000, v28
	v_pk_mul_f32 v[26:27], v[42:43], v[66:67] op_sel_hi:[0,1]
	v_fmac_f32_e32 v78, v61, v28
	v_lshlrev_b32_e32 v28, 16, v29
	v_fmac_f32_e32 v45, v26, v28
	v_and_b32_e32 v26, 0xffff0000, v29
	v_fmac_f32_e32 v43, v27, v26
	v_fmac_f32_e32 v83, v68, v70
	v_fmac_f32_e32 v79, v60, v64
	v_pk_mul_f32 v[66:67], v[42:43], v[36:37] op_sel_hi:[0,1]
	v_pk_mul_f32 v[70:71], v[42:43], v[34:35] op_sel_hi:[0,1]
	v_pk_mul_f32 v[60:61], v[42:43], v[32:33] op_sel_hi:[0,1]
	v_pk_mul_f32 v[64:65], v[42:43], v[30:31] op_sel_hi:[0,1]
	global_load_dwordx4 v[26:29], v41, s[8:9] offset:48
	global_load_dwordx4 v[30:33], v41, s[8:9] offset:32
	global_load_dwordx4 v[34:37], v41, s[8:9] offset:16
	global_load_dwordx4 v[72:75], v41, s[8:9]
	s_mov_b32 s8, 0
	s_ashr_i32 s9, s8, 31
	s_lshl_b64 s[8:9], s[8:9], 3
	s_add_u32 s8, s0, s8
	s_addc_u32 s9, s1, s9
	s_load_dwordx2 s[8:9], s[8:9], 0x90
	s_waitcnt lgkmcnt(0)
	s_add_u32 s8, s8, s22
	s_addc_u32 s9, s9, s23
	s_waitcnt vmcnt(2)
	v_pk_mul_f32 v[76:77], v[40:41], v[30:31] op_sel_hi:[0,1]
	s_waitcnt vmcnt(1)
	v_pk_mul_f32 v[34:35], v[40:41], v[34:35] op_sel_hi:[0,1]
	s_waitcnt vmcnt(0)
	v_pk_mul_f32 v[68:69], v[40:41], v[74:75] op_sel_hi:[0,1]
	v_pk_mul_f32 v[72:73], v[40:41], v[72:73] op_sel_hi:[0,1]
	v_lshlrev_b32_e32 v74, 16, v22
	v_and_b32_e32 v22, 0xffff0000, v22
	v_fmac_f32_e32 v82, v73, v22
	v_lshlrev_b32_e32 v22, 16, v23
	v_fmac_f32_e32 v81, v68, v22
	v_and_b32_e32 v22, 0xffff0000, v23
	v_fmac_f32_e32 v80, v69, v22
	v_pk_mul_f32 v[22:23], v[40:41], v[36:37] op_sel_hi:[0,1]
	v_lshlrev_b32_e32 v36, 16, v24
	v_and_b32_e32 v24, 0xffff0000, v24
	v_fmac_f32_e32 v78, v35, v24
	v_lshlrev_b32_e32 v24, 16, v25
	v_fmac_f32_e32 v45, v22, v24
	v_and_b32_e32 v22, 0xffff0000, v25
	v_fmac_f32_e32 v83, v72, v74
	v_fmac_f32_e32 v79, v34, v36
	v_fmac_f32_e32 v43, v23, v22
	v_pk_mul_f32 v[74:75], v[40:41], v[32:33] op_sel_hi:[0,1]
	v_pk_mul_f32 v[68:69], v[40:41], v[28:29] op_sel_hi:[0,1]
	v_pk_mul_f32 v[72:73], v[40:41], v[26:27] op_sel_hi:[0,1]
	global_load_dwordx4 v[22:25], v41, s[8:9] offset:48
	global_load_dwordx4 v[26:29], v41, s[8:9] offset:32
	global_load_dwordx4 v[30:33], v41, s[8:9] offset:16
	global_load_dwordx4 v[34:37], v41, s[8:9]
	s_waitcnt vmcnt(2)
	v_pk_mul_f32 v[26:27], v[38:39], v[26:27] op_sel_hi:[0,1]
	s_waitcnt vmcnt(1)
	v_pk_mul_f32 v[30:31], v[38:39], v[30:31] op_sel_hi:[0,1]
	s_waitcnt vmcnt(0)
	v_pk_mul_f32 v[34:35], v[38:39], v[34:35] op_sel_hi:[0,1]
	v_pk_mul_f32 v[36:37], v[38:39], v[36:37] op_sel_hi:[0,1]
	v_fmac_f32_e32 v82, v35, v18
	v_lshlrev_b32_e32 v18, 16, v19
	v_fmac_f32_e32 v81, v36, v18
	v_and_b32_e32 v18, 0xffff0000, v19
	v_fmac_f32_e32 v80, v37, v18
	v_pk_mul_f32 v[18:19], v[38:39], v[32:33] op_sel_hi:[0,1]
	v_lshlrev_b32_e32 v32, 16, v20
	v_and_b32_e32 v20, 0xffff0000, v20
	v_fmac_f32_e32 v83, v34, v84
	v_fmac_f32_e32 v78, v31, v20
	v_lshlrev_b32_e32 v20, 16, v21
	v_fmac_f32_e32 v45, v18, v20
	v_and_b32_e32 v18, 0xffff0000, v21
	v_pk_mul_f32 v[20:21], v[38:39], v[22:23] op_sel_hi:[0,1]
	v_mul_f32_e32 v22, 0xbfb8aa3b, v83
	v_exp_f32_e32 v22, v22
	v_fmac_f32_e32 v79, v30, v32
	v_fmac_f32_e32 v43, v19, v18
	v_and_b32_e32 v23, 0xffff0000, v0
	v_add_f32_e32 v22, 1.0, v22
	v_rcp_f32_e32 v22, v22
	v_pk_mul_f32 v[18:19], v[38:39], v[24:25] op_sel_hi:[0,1]
	v_and_b32_e32 v25, 0xffff0000, v4
	v_lshlrev_b32_e32 v24, 16, v4
	v_mul_f32_e32 v30, v83, v22
	v_mul_f32_e32 v22, 0xbfb8aa3b, v82
	v_exp_f32_e32 v22, v22
	v_lshlrev_b32_e32 v4, 16, v9
	v_pk_mul_f32 v[28:29], v[38:39], v[28:29] op_sel_hi:[0,1]
	v_add_f32_e32 v22, 1.0, v22
	v_rcp_f32_e32 v22, v22
	s_nop 0
	v_mul_f32_e32 v31, v82, v22
	v_mul_f32_e32 v22, 0xbfb8aa3b, v81
	v_exp_f32_e32 v22, v22
	s_nop 0
	v_add_f32_e32 v22, 1.0, v22
	v_rcp_f32_e32 v22, v22
	s_nop 0
	v_mul_f32_e32 v32, v81, v22
	v_mul_f32_e32 v22, 0xbfb8aa3b, v80
	v_exp_f32_e32 v22, v22
	s_nop 0
	v_add_f32_e32 v22, 1.0, v22
	v_rcp_f32_e32 v22, v22
	s_nop 0
	v_mul_f32_e32 v33, v80, v22
	v_mul_f32_e32 v22, 0xbfb8aa3b, v79
	v_exp_f32_e32 v22, v22
	s_nop 0
	v_add_f32_e32 v22, 1.0, v22
	v_rcp_f32_e32 v22, v22
	s_nop 0
	v_mul_f32_e32 v34, v79, v22
	v_mul_f32_e32 v22, 0xbfb8aa3b, v78
	v_exp_f32_e32 v22, v22
	s_nop 0
	v_add_f32_e32 v22, 1.0, v22
	v_rcp_f32_e32 v22, v22
	s_nop 0
	v_mul_f32_e32 v35, v78, v22
	v_mul_f32_e32 v22, 0xbfb8aa3b, v45
	v_exp_f32_e32 v22, v22
	s_nop 0
	v_add_f32_e32 v22, 1.0, v22
	v_rcp_f32_e32 v22, v22
	s_nop 0
	v_mul_f32_e32 v36, v45, v22
	v_mul_f32_e32 v22, 0xbfb8aa3b, v43
	v_exp_f32_e32 v22, v22
	s_nop 0
	v_add_f32_e32 v22, 1.0, v22
	v_rcp_f32_e32 v22, v22
	s_nop 0
	v_mul_f32_e32 v37, v43, v22
	v_lshlrev_b32_e32 v22, 16, v0
	v_pk_fma_f32 v[22:23], v[62:63], v[22:23], 0 op_sel_hi:[1,1,0]
	v_mul_f32_e32 v43, v31, v31
	v_pk_fma_f32 v[22:23], v[70:71], v[24:25], v[22:23]
	v_and_b32_e32 v25, 0xffff0000, v8
	v_lshlrev_b32_e32 v24, 16, v8
	v_pk_fma_f32 v[22:23], v[76:77], v[24:25], v[22:23]
	v_and_b32_e32 v25, 0xffff0000, v12
	v_lshlrev_b32_e32 v24, 16, v12
	v_pk_fma_f32 v[22:23], v[26:27], v[24:25], v[22:23]
	v_fmac_f32_e32 v43, v30, v30
	v_mul_f32_e32 v0, 0xbfb8aa3b, v22
	v_exp_f32_e32 v0, v0
	v_fmac_f32_e32 v43, v32, v32
	v_fmac_f32_e32 v43, v33, v33
	v_fmac_f32_e32 v43, v34, v34
	v_add_f32_e32 v0, 1.0, v0
	v_rcp_f32_e32 v24, v0
	v_mul_f32_e32 v0, 0xbfb8aa3b, v23
	v_exp_f32_e32 v0, v0
	v_fmac_f32_e32 v43, v35, v35
	v_fmac_f32_e32 v43, v36, v36
	v_fmac_f32_e32 v43, v37, v37
	v_add_f32_e32 v0, 1.0, v0
	v_rcp_f32_e32 v25, v0
	s_nop 0
	v_pk_mul_f32 v[22:23], v[22:23], v[24:25]
	s_nop 0
	v_pk_mul_f32 v[24:25], v[22:23], v[22:23]
	s_nop 0
	v_add_f32_e32 v0, v24, v43
	v_add_f32_e32 v8, v25, v0
	v_and_b32_e32 v25, 0xffff0000, v1
	v_lshlrev_b32_e32 v24, 16, v1
	v_pk_fma_f32 v[0:1], v[58:59], v[24:25], 0 op_sel_hi:[1,1,0]
	v_and_b32_e32 v25, 0xffff0000, v5
	v_lshlrev_b32_e32 v24, 16, v5
	v_pk_fma_f32 v[0:1], v[66:67], v[24:25], v[0:1]
	v_and_b32_e32 v5, 0xffff0000, v9
	v_pk_fma_f32 v[0:1], v[74:75], v[4:5], v[0:1]
	v_and_b32_e32 v5, 0xffff0000, v13
	v_lshlrev_b32_e32 v4, 16, v13
	v_pk_fma_f32 v[0:1], v[28:29], v[4:5], v[0:1]
	v_and_b32_e32 v9, 0xffff0000, v6
	v_mul_f32_e32 v4, 0xbfb8aa3b, v0
	v_mul_f32_e32 v5, 0xbfb8aa3b, v1
	v_exp_f32_e32 v4, v4
	v_exp_f32_e32 v5, v5
	v_add_f32_e32 v4, 1.0, v4
	v_add_f32_e32 v5, 1.0, v5
	v_rcp_f32_e32 v4, v4
	v_rcp_f32_e32 v5, v5
	s_nop 0
	v_pk_mul_f32 v[0:1], v[0:1], v[4:5]
	s_nop 0
	v_pk_mul_f32 v[4:5], v[0:1], v[0:1]
	s_nop 0
	v_add_f32_e32 v4, v4, v8
	v_add_f32_e32 v12, v5, v4
	v_and_b32_e32 v5, 0xffff0000, v2
	v_lshlrev_b32_e32 v4, 16, v2
	v_pk_fma_f32 v[4:5], v[56:57], v[4:5], 0 op_sel_hi:[1,1,0]
	v_lshlrev_b32_e32 v8, 16, v6
	v_pk_fma_f32 v[4:5], v[64:65], v[8:9], v[4:5]
	v_and_b32_e32 v9, 0xffff0000, v10
	v_lshlrev_b32_e32 v8, 16, v10
	v_pk_fma_f32 v[4:5], v[72:73], v[8:9], v[4:5]
	v_and_b32_e32 v9, 0xffff0000, v14
	v_lshlrev_b32_e32 v8, 16, v14
	v_pk_fma_f32 v[4:5], v[20:21], v[8:9], v[4:5]
	v_lshlrev_b32_e32 v6, 16, v11
	v_mul_f32_e32 v2, 0xbfb8aa3b, v4
	v_exp_f32_e32 v2, v2
	s_nop 0
	v_add_f32_e32 v2, 1.0, v2
	v_rcp_f32_e32 v8, v2
	v_mul_f32_e32 v2, 0xbfb8aa3b, v5
	v_exp_f32_e32 v2, v2
	s_nop 0
	v_add_f32_e32 v2, 1.0, v2
	v_rcp_f32_e32 v9, v2
	s_nop 0
	v_pk_mul_f32 v[4:5], v[4:5], v[8:9]
	s_nop 0
	v_pk_mul_f32 v[8:9], v[4:5], v[4:5]
	s_nop 0
	v_add_f32_e32 v2, v8, v12
	v_add_f32_e32 v10, v9, v2
	v_and_b32_e32 v9, 0xffff0000, v3
	v_lshlrev_b32_e32 v8, 16, v3
	v_pk_fma_f32 v[2:3], v[54:55], v[8:9], 0 op_sel_hi:[1,1,0]
	v_and_b32_e32 v9, 0xffff0000, v7
	v_lshlrev_b32_e32 v8, 16, v7
	v_pk_fma_f32 v[2:3], v[60:61], v[8:9], v[2:3]
	v_and_b32_e32 v7, 0xffff0000, v11
	v_pk_fma_f32 v[2:3], v[68:69], v[6:7], v[2:3]
	v_and_b32_e32 v7, 0xffff0000, v15
	v_lshlrev_b32_e32 v6, 16, v15
	v_pk_fma_f32 v[2:3], v[18:19], v[6:7], v[2:3]
	v_add_u32_e32 v8, 64, v111
	v_mul_f32_e32 v6, 0xbfb8aa3b, v3
	v_exp_f32_e32 v6, v6
	s_nop 0
	v_add_f32_e32 v6, 1.0, v6
	v_rcp_f32_e32 v7, v6
	v_mul_f32_e32 v6, 0xbfb8aa3b, v2
	v_exp_f32_e32 v6, v6
	s_nop 0
	v_add_f32_e32 v6, 1.0, v6
	v_rcp_f32_e32 v6, v6
	s_nop 0
	v_pk_mul_f32 v[2:3], v[2:3], v[6:7]
	s_nop 0
	v_pk_mul_f32 v[6:7], v[2:3], v[2:3]
	s_nop 0
	v_add_f32_e32 v6, v6, v10
	v_add_f32_e32 v6, v7, v6
	v_xor_b32_e32 v7, 1, v234
	v_cmp_lt_i32_e32 vcc, v7, v8
	s_nop 1
	v_cndmask_b32_e32 v7, v234, v7, vcc
	v_lshlrev_b32_e32 v45, 2, v7
	ds_bpermute_b32 v7, v45, v6
	s_waitcnt lgkmcnt(0)
	v_add_f32_e32 v6, v6, v7
	v_xor_b32_e32 v7, 2, v234
	v_cmp_lt_i32_e32 vcc, v7, v8
	s_nop 1
	v_cndmask_b32_e32 v7, v234, v7, vcc
	v_lshlrev_b32_e32 v112, 2, v7
	ds_bpermute_b32 v7, v112, v6
	s_waitcnt lgkmcnt(0)
	v_add_f32_e32 v6, v6, v7
	v_xor_b32_e32 v7, 4, v234
	v_cmp_lt_i32_e32 vcc, v7, v8
	s_nop 1
	v_cndmask_b32_e32 v7, v234, v7, vcc
	v_lshlrev_b32_e32 v113, 2, v7
	ds_bpermute_b32 v7, v113, v6
	s_waitcnt lgkmcnt(0)
	v_add_f32_e32 v6, v6, v7
	v_add_f32_e32 v6, 0x358637bd, v6
	v_cmp_gt_f32_e32 vcc, s33, v6
	v_mul_f32_e32 v7, 0x4b800000, v6
	s_nop 0
	v_cndmask_b32_e32 v6, v6, v7, vcc
	v_rsq_f32_e32 v6, v6
	s_nop 0
	v_mul_f32_e32 v7, 0x45800000, v6
	v_cndmask_b32_e32 v6, v6, v7, vcc
	v_mul_f32_e32 v6, 0x3db504f3, v6
	v_mul_f32_e32 v7, v30, v6
	v_mul_f32_e32 v8, v31, v6
	v_mul_f32_e32 v9, v32, v6
	v_mul_f32_e32 v10, v33, v6
	v_mul_f32_e32 v11, v34, v6
	v_mul_f32_e32 v12, v35, v6
	v_mul_f32_e32 v13, v36, v6
	v_mul_f32_e32 v14, v37, v6
	v_mul_f32_e32 v15, v22, v6
	v_mul_f32_e32 v18, v23, v6
	v_mul_f32_e32 v0, v0, v6
	v_mul_f32_e32 v1, v1, v6
	v_mul_f32_e32 v4, v4, v6
	v_mul_f32_e32 v5, v5, v6
	v_mul_f32_e32 v2, v2, v6
	v_mul_f32_e32 v3, v3, v6
	v_lshlrev_b32_e32 v6, 5, v105
	v_add3_u32 v43, 0, v6, v109
	v_cvt_pk_bf16_f32 v6, v7, v8
	v_add_u32_e32 v8, 0x4400, v43
	v_cvt_pk_bf16_f32 v7, v9, v10
	ds_write2_b32 v8, v6, v7 offset1:1
	v_cvt_pk_bf16_f32 v6, v11, v12
	v_cvt_pk_bf16_f32 v0, v0, v1
	v_cvt_pk_bf16_f32 v7, v13, v14
	ds_write2_b32 v8, v6, v7 offset0:2 offset1:3
	v_cvt_pk_bf16_f32 v6, v15, v18
	ds_write2_b32 v8, v6, v0 offset0:4 offset1:5
	v_cvt_pk_bf16_f32 v0, v4, v5
	v_cvt_pk_bf16_f32 v1, v2, v3
	ds_write2_b32 v8, v0, v1 offset0:6 offset1:7
	v_lshl_add_u64 v[0:1], v[46:47], 0, v[16:17]
	flat_load_dwordx4 v[30:33], v[0:1]
	flat_load_dwordx4 v[12:15], v[0:1] offset:16
	v_lshl_add_u64 v[0:1], v[48:49], 0, v[16:17]
	flat_load_dwordx4 v[26:29], v[0:1]
	flat_load_dwordx4 v[8:11], v[0:1] offset:16
	v_lshl_add_u64 v[0:1], v[50:51], 0, v[16:17]
	flat_load_dwordx4 v[22:25], v[0:1]
	flat_load_dwordx4 v[4:7], v[0:1] offset:16
	v_lshl_add_u64 v[0:1], v[52:53], 0, v[16:17]
	flat_load_dwordx4 v[18:21], v[0:1]
	s_nop 0
	flat_load_dwordx4 v[0:3], v[0:1] offset:16
	s_mov_b32 s8, 0
	s_ashr_i32 s9, s8, 31
	s_lshl_b64 s[8:9], s[8:9], 3
	s_add_u32 s8, s0, s8
	s_addc_u32 s9, s1, s9
	s_load_dwordx2 s[8:9], s[8:9], 0x90
	s_waitcnt lgkmcnt(0)
	s_add_u32 s8, s8, s15
	s_addc_u32 s9, s9, s14
	global_load_dwordx4 v[58:61], v41, s[8:9] offset:2096
	global_load_dwordx4 v[62:65], v41, s[8:9] offset:2080
	global_load_dwordx4 v[34:37], v41, s[8:9] offset:2064
	global_load_dwordx4 v[54:57], v41, s[8:9] offset:2048
	s_mov_b32 s8, 0
	s_ashr_i32 s9, s8, 31
	s_lshl_b64 s[8:9], s[8:9], 3
	s_add_u32 s8, s0, s8
	s_addc_u32 s9, s1, s9
	s_load_dwordx2 s[8:9], s[8:9], 0x90
	s_waitcnt lgkmcnt(0)
	s_add_u32 s8, s8, s16
	s_addc_u32 s9, s9, s17
	s_waitcnt vmcnt(0)
	v_pk_mul_f32 v[92:93], v[44:45], v[60:61] op_sel_hi:[0,1]
	v_pk_mul_f32 v[74:75], v[44:45], v[58:59] op_sel_hi:[0,1]
	v_pk_mul_f32 v[66:67], v[44:45], v[34:35] op_sel_hi:[0,1]
	v_pk_mul_f32 v[78:79], v[44:45], v[54:55] op_sel_hi:[0,1]
	v_pk_mul_f32 v[34:35], v[44:45], v[64:65] op_sel_hi:[0,1]
	v_pk_mul_f32 v[54:55], v[44:45], v[62:63] op_sel_hi:[0,1]
	global_load_dwordx4 v[82:85], v41, s[8:9] offset:2096
	global_load_dwordx4 v[58:61], v41, s[8:9] offset:2080
	global_load_dwordx4 v[88:91], v41, s[8:9] offset:2064
	global_load_dwordx4 v[62:65], v41, s[8:9] offset:2048
	s_mov_b32 s8, 0
	s_ashr_i32 s9, s8, 31
	s_lshl_b64 s[8:9], s[8:9], 3
	s_add_u32 s8, s0, s8
	s_addc_u32 s9, s1, s9
	s_load_dwordx2 s[8:9], s[8:9], 0x90
	v_pk_mul_f32 v[70:71], v[44:45], v[56:57] op_sel_hi:[0,1]
	v_pk_mul_f32 v[56:57], v[44:45], v[36:37] op_sel_hi:[0,1]
	s_waitcnt lgkmcnt(0)
	s_add_u32 s8, s8, s18
	s_addc_u32 s9, s9, s19
	global_load_dwordx4 v[100:103], v41, s[8:9] offset:2096
	global_load_dwordx4 v[114:117], v41, s[8:9] offset:2080
	global_load_dwordx4 v[118:121], v41, s[8:9] offset:2064
	global_load_dwordx4 v[94:97], v41, s[8:9] offset:2048
	s_mov_b32 s8, 0
	s_ashr_i32 s9, s8, 31
	s_lshl_b64 s[8:9], s[8:9], 3
	s_add_u32 s8, s0, s8
	s_addc_u32 s9, s1, s9
	s_load_dwordx2 s[8:9], s[8:9], 0x90
	s_waitcnt lgkmcnt(0)
	s_add_u32 s8, s8, s22
	s_addc_u32 s9, s9, s23
	s_waitcnt vmcnt(7)
	v_pk_mul_f32 v[98:99], v[42:43], v[84:85] op_sel_hi:[0,1]
	s_waitcnt vmcnt(6)
	v_pk_mul_f32 v[36:37], v[42:43], v[60:61] op_sel_hi:[0,1]
	v_pk_mul_f32 v[60:61], v[42:43], v[58:59] op_sel_hi:[0,1]
	s_waitcnt vmcnt(4)
	v_pk_mul_f32 v[80:81], v[42:43], v[64:65] op_sel_hi:[0,1]
	v_pk_mul_f32 v[84:85], v[42:43], v[82:83] op_sel_hi:[0,1]
	v_pk_mul_f32 v[86:87], v[42:43], v[62:63] op_sel_hi:[0,1]
	v_pk_mul_f32 v[62:63], v[42:43], v[90:91] op_sel_hi:[0,1]
	v_pk_mul_f32 v[72:73], v[42:43], v[88:89] op_sel_hi:[0,1]
	s_waitcnt vmcnt(3)
	v_pk_mul_f32 v[130:131], v[40:41], v[100:101] op_sel_hi:[0,1]
	s_waitcnt vmcnt(2)
	v_pk_mul_f32 v[58:59], v[40:41], v[116:117] op_sel_hi:[0,1]
	s_waitcnt vmcnt(1)
	v_pk_mul_f32 v[68:69], v[40:41], v[120:121] op_sel_hi:[0,1]
	v_pk_mul_f32 v[82:83], v[40:41], v[118:119] op_sel_hi:[0,1]
	v_pk_mul_f32 v[64:65], v[40:41], v[114:115] op_sel_hi:[0,1]
	global_load_dwordx4 v[114:117], v41, s[8:9] offset:2096
	global_load_dwordx4 v[118:121], v41, s[8:9] offset:2080
	global_load_dwordx4 v[122:125], v41, s[8:9] offset:2064
	global_load_dwordx4 v[126:129], v41, s[8:9] offset:2048
	v_pk_mul_f32 v[102:103], v[40:41], v[102:103] op_sel_hi:[0,1]
	s_waitcnt vmcnt(4)
	v_pk_mul_f32 v[88:89], v[40:41], v[96:97] op_sel_hi:[0,1]
	v_pk_mul_f32 v[96:97], v[40:41], v[94:95] op_sel_hi:[0,1]
	s_waitcnt vmcnt(3)
	v_pk_mul_f32 v[114:115], v[38:39], v[114:115] op_sel_hi:[0,1]
	s_waitcnt vmcnt(2)
	v_pk_mul_f32 v[90:91], v[38:39], v[118:119] op_sel_hi:[0,1]
	v_and_b32_e32 v119, 0xffff0000, v14
	v_lshlrev_b32_e32 v118, 16, v14
	v_pk_fma_f32 v[74:75], v[74:75], v[118:119], 0 op_sel_hi:[1,1,0]
	v_and_b32_e32 v119, 0xffff0000, v10
	v_lshlrev_b32_e32 v118, 16, v10
	v_pk_fma_f32 v[74:75], v[84:85], v[118:119], v[74:75]
	v_and_b32_e32 v85, 0xffff0000, v6
	v_lshlrev_b32_e32 v84, 16, v6
	v_pk_fma_f32 v[74:75], v[130:131], v[84:85], v[74:75]
	v_and_b32_e32 v85, 0xffff0000, v2
	v_lshlrev_b32_e32 v84, 16, v2
	v_pk_fma_f32 v[74:75], v[114:115], v[84:85], v[74:75]
	v_and_b32_e32 v115, 0xffff0000, v15
	v_mul_f32_e32 v2, 0xbfb8aa3b, v74
	v_exp_f32_e32 v2, v2
	v_lshlrev_b32_e32 v114, 16, v15
	v_pk_fma_f32 v[14:15], v[92:93], v[114:115], 0 op_sel_hi:[1,1,0]
	v_and_b32_e32 v93, 0xffff0000, v11
	v_add_f32_e32 v2, 1.0, v2
	v_rcp_f32_e32 v84, v2
	v_mul_f32_e32 v2, 0xbfb8aa3b, v75
	v_exp_f32_e32 v2, v2
	v_lshlrev_b32_e32 v92, 16, v11
	v_pk_fma_f32 v[10:11], v[98:99], v[92:93], v[14:15]
	v_and_b32_e32 v15, 0xffff0000, v7
	v_lshlrev_b32_e32 v14, 16, v7
	v_pk_mul_f32 v[116:117], v[38:39], v[116:117] op_sel_hi:[0,1]
	v_add_f32_e32 v2, 1.0, v2
	v_pk_fma_f32 v[6:7], v[102:103], v[14:15], v[10:11]
	v_and_b32_e32 v11, 0xffff0000, v3
	v_lshlrev_b32_e32 v10, 16, v3
	v_rcp_f32_e32 v85, v2
	v_pk_fma_f32 v[2:3], v[116:117], v[10:11], v[6:7]
	v_lshlrev_b32_e32 v10, 16, v30
	v_and_b32_e32 v11, 0xffff0000, v30
	v_lshlrev_b32_e32 v30, 16, v31
	v_and_b32_e32 v31, 0xffff0000, v31
	v_pk_fma_f32 v[10:11], v[78:79], v[10:11], 0 op_sel_hi:[1,1,0]
	v_lshlrev_b32_e32 v14, 16, v26
	v_and_b32_e32 v15, 0xffff0000, v26
	v_pk_fma_f32 v[30:31], v[70:71], v[30:31], 0 op_sel_hi:[1,1,0]
	v_lshlrev_b32_e32 v26, 16, v27
	v_and_b32_e32 v27, 0xffff0000, v27
	v_pk_fma_f32 v[10:11], v[86:87], v[14:15], v[10:11]
	v_lshlrev_b32_e32 v14, 16, v22
	v_and_b32_e32 v15, 0xffff0000, v22
	v_pk_fma_f32 v[26:27], v[80:81], v[26:27], v[30:31]
	v_lshlrev_b32_e32 v22, 16, v23
	v_and_b32_e32 v23, 0xffff0000, v23
	s_waitcnt vmcnt(0)
	v_pk_mul_f32 v[128:129], v[38:39], v[128:129] op_sel_hi:[0,1]
	v_pk_fma_f32 v[10:11], v[96:97], v[14:15], v[10:11]
	v_lshlrev_b32_e32 v14, 16, v18
	v_and_b32_e32 v15, 0xffff0000, v18
	v_pk_fma_f32 v[22:23], v[88:89], v[22:23], v[26:27]
	v_lshlrev_b32_e32 v18, 16, v19
	v_and_b32_e32 v19, 0xffff0000, v19
	v_pk_fma_f32 v[18:19], v[128:129], v[18:19], v[22:23]
	v_lshlrev_b32_e32 v26, 16, v32
	v_mul_f32_e32 v16, 0xbfb8aa3b, v18
	v_exp_f32_e32 v16, v16
	v_and_b32_e32 v27, 0xffff0000, v32
	v_pk_fma_f32 v[26:27], v[66:67], v[26:27], 0 op_sel_hi:[1,1,0]
	v_lshlrev_b32_e32 v30, 16, v28
	v_add_f32_e32 v16, 1.0, v16
	v_rcp_f32_e32 v22, v16
	v_mul_f32_e32 v16, 0xbfb8aa3b, v19
	v_exp_f32_e32 v16, v16
	v_and_b32_e32 v31, 0xffff0000, v28
	v_pk_fma_f32 v[26:27], v[72:73], v[30:31], v[26:27]
	v_lshlrev_b32_e32 v30, 16, v24
	v_and_b32_e32 v31, 0xffff0000, v24
	v_pk_mul_f32 v[100:101], v[38:39], v[122:123] op_sel_hi:[0,1]
	v_pk_fma_f32 v[26:27], v[82:83], v[30:31], v[26:27]
	v_lshlrev_b32_e32 v30, 16, v20
	v_and_b32_e32 v31, 0xffff0000, v20
	v_add_f32_e32 v16, 1.0, v16
	v_pk_fma_f32 v[26:27], v[100:101], v[30:31], v[26:27]
	v_rcp_f32_e32 v23, v16
	v_mul_f32_e32 v16, 0xbfb8aa3b, v26
	v_lshlrev_b32_e32 v32, 16, v33
	v_and_b32_e32 v33, 0xffff0000, v33
	v_exp_f32_e32 v16, v16
	v_pk_fma_f32 v[32:33], v[56:57], v[32:33], 0 op_sel_hi:[1,1,0]
	v_lshlrev_b32_e32 v28, 16, v29
	v_and_b32_e32 v29, 0xffff0000, v29
	v_pk_fma_f32 v[28:29], v[62:63], v[28:29], v[32:33]
	v_lshlrev_b32_e32 v24, 16, v25
	v_and_b32_e32 v25, 0xffff0000, v25
	v_pk_fma_f32 v[24:25], v[68:69], v[24:25], v[28:29]
	v_lshlrev_b32_e32 v28, 16, v12
	v_and_b32_e32 v29, 0xffff0000, v12
	v_pk_fma_f32 v[28:29], v[54:55], v[28:29], 0 op_sel_hi:[1,1,0]
	v_lshlrev_b32_e32 v32, 16, v8
	v_and_b32_e32 v33, 0xffff0000, v8
	v_add_f32_e32 v16, 1.0, v16
	v_pk_fma_f32 v[28:29], v[60:61], v[32:33], v[28:29]
	v_lshlrev_b32_e32 v32, 16, v4
	v_and_b32_e32 v33, 0xffff0000, v4
	v_rcp_f32_e32 v30, v16
	v_mul_f32_e32 v16, 0xbfb8aa3b, v27
	v_pk_fma_f32 v[28:29], v[64:65], v[32:33], v[28:29]
	v_lshlrev_b32_e32 v32, 16, v0
	v_and_b32_e32 v33, 0xffff0000, v0
	v_exp_f32_e32 v16, v16
	v_pk_fma_f32 v[28:29], v[90:91], v[32:33], v[28:29]
	v_pk_mul_f32 v[94:95], v[38:39], v[124:125] op_sel_hi:[0,1]
	v_mul_f32_e32 v0, 0xbfb8aa3b, v28
	v_exp_f32_e32 v0, v0
	v_lshlrev_b32_e32 v20, 16, v21
	v_and_b32_e32 v21, 0xffff0000, v21
	v_pk_mul_f32 v[126:127], v[38:39], v[126:127] op_sel_hi:[0,1]
	v_add_f32_e32 v16, 1.0, v16
	v_pk_fma_f32 v[20:21], v[94:95], v[20:21], v[24:25]
	v_pk_fma_f32 v[10:11], v[126:127], v[14:15], v[10:11]
	v_rcp_f32_e32 v31, v16
	v_mul_f32_e32 v16, 0xbfb8aa3b, v20
	v_mul_f32_e32 v14, 0xbfb8aa3b, v10
	v_mul_f32_e32 v15, 0xbfb8aa3b, v11
	v_exp_f32_e32 v16, v16
	v_add_f32_e32 v0, 1.0, v0
	v_exp_f32_e32 v14, v14
	v_exp_f32_e32 v15, v15
	v_rcp_f32_e32 v32, v0
	v_mul_f32_e32 v0, 0xbfb8aa3b, v29
	v_exp_f32_e32 v0, v0
	v_add_f32_e32 v16, 1.0, v16
	v_lshlrev_b32_e32 v12, 16, v13
	v_and_b32_e32 v13, 0xffff0000, v13
	v_add_f32_e32 v14, 1.0, v14
	v_add_f32_e32 v15, 1.0, v15
	v_rcp_f32_e32 v24, v16
	v_mul_f32_e32 v16, 0xbfb8aa3b, v21
	v_pk_fma_f32 v[12:13], v[34:35], v[12:13], 0 op_sel_hi:[1,1,0]
	v_lshlrev_b32_e32 v8, 16, v9
	v_and_b32_e32 v9, 0xffff0000, v9
	v_rcp_f32_e32 v14, v14
	v_rcp_f32_e32 v15, v15
	v_exp_f32_e32 v16, v16
	v_add_f32_e32 v0, 1.0, v0
	v_pk_fma_f32 v[8:9], v[36:37], v[8:9], v[12:13]
	v_lshlrev_b32_e32 v4, 16, v5
	v_and_b32_e32 v5, 0xffff0000, v5
	v_pk_mul_f32 v[76:77], v[38:39], v[120:121] op_sel_hi:[0,1]
	v_mul_f32_e32 v6, 0xbfb8aa3b, v3
	v_rcp_f32_e32 v33, v0
	v_pk_fma_f32 v[4:5], v[58:59], v[4:5], v[8:9]
	v_lshlrev_b32_e32 v0, 16, v1
	v_and_b32_e32 v1, 0xffff0000, v1
	v_exp_f32_e32 v6, v6
	v_pk_fma_f32 v[0:1], v[76:77], v[0:1], v[4:5]
	v_pk_mul_f32 v[10:11], v[10:11], v[14:15]
	v_mul_f32_e32 v4, 0xbfb8aa3b, v0
	v_mul_f32_e32 v5, 0xbfb8aa3b, v1
	v_add_f32_e32 v16, 1.0, v16
	v_exp_f32_e32 v4, v4
	v_exp_f32_e32 v5, v5
	v_pk_mul_f32 v[14:15], v[10:11], v[10:11]
	v_pk_mul_f32 v[18:19], v[18:19], v[22:23]
	v_rcp_f32_e32 v25, v16
	v_add_f32_e32 v6, 1.0, v6
	v_pk_mul_f32 v[22:23], v[18:19], v[18:19]
	v_add_f32_e32 v8, v14, v15
	v_rcp_f32_e32 v7, v6
	v_mul_f32_e32 v6, 0xbfb8aa3b, v2
	v_pk_mul_f32 v[26:27], v[26:27], v[30:31]
	v_add_f32_e32 v8, v22, v8
	v_exp_f32_e32 v6, v6
	v_pk_mul_f32 v[30:31], v[26:27], v[26:27]
	v_add_f32_e32 v4, 1.0, v4
	v_add_f32_e32 v5, 1.0, v5
	v_add_f32_e32 v8, v23, v8
	v_pk_mul_f32 v[20:21], v[20:21], v[24:25]
	v_rcp_f32_e32 v4, v4
	v_rcp_f32_e32 v5, v5
	v_add_f32_e32 v8, v30, v8
	v_pk_mul_f32 v[24:25], v[20:21], v[20:21]
	v_add_f32_e32 v8, v31, v8
	v_pk_mul_f32 v[28:29], v[28:29], v[32:33]
	v_add_f32_e32 v8, v24, v8
	v_add_f32_e32 v6, 1.0, v6
	v_pk_mul_f32 v[32:33], v[28:29], v[28:29]
	v_add_f32_e32 v8, v25, v8
	v_rcp_f32_e32 v6, v6
	v_pk_mul_f32 v[0:1], v[0:1], v[4:5]
	v_add_f32_e32 v8, v32, v8
	v_pk_mul_f32 v[4:5], v[0:1], v[0:1]
	v_add_f32_e32 v8, v33, v8
	v_pk_mul_f32 v[74:75], v[74:75], v[84:85]
	v_add_f32_e32 v4, v4, v8
	v_pk_mul_f32 v[84:85], v[74:75], v[74:75]
	v_add_f32_e32 v4, v5, v4
	v_pk_mul_f32 v[2:3], v[2:3], v[6:7]
	v_add_f32_e32 v4, v84, v4
	v_pk_mul_f32 v[6:7], v[2:3], v[2:3]
	v_add_f32_e32 v4, v85, v4
	v_add_f32_e32 v4, v6, v4
	v_add_f32_e32 v4, v7, v4
	ds_bpermute_b32 v5, v45, v4
	v_or_b32_e32 v34, 0x400, v39
	s_waitcnt lgkmcnt(0)
	v_add_f32_e32 v4, v4, v5
	ds_bpermute_b32 v5, v112, v4
	s_waitcnt lgkmcnt(0)
	v_add_f32_e32 v4, v4, v5
	ds_bpermute_b32 v5, v113, v4
	s_waitcnt lgkmcnt(0)
	v_add_f32_e32 v4, v4, v5
	v_add_f32_e32 v4, 0x358637bd, v4
	v_cmp_gt_f32_e32 vcc, s33, v4
	v_mul_f32_e32 v5, 0x4b800000, v4
	s_nop 0
	v_cndmask_b32_e32 v4, v4, v5, vcc
	v_rsq_f32_e32 v4, v4
	s_nop 0
	v_mul_f32_e32 v5, 0x45800000, v4
	v_cndmask_b32_e32 v16, v4, v5, vcc
	v_pk_mul_f32 v[4:5], v[10:11], v[16:17] op_sel_hi:[1,0]
	v_pk_mul_f32 v[6:7], v[18:19], v[16:17] op_sel_hi:[1,0]
	v_pk_mul_f32 v[8:9], v[26:27], v[16:17] op_sel_hi:[1,0]
	v_pk_mul_f32 v[10:11], v[20:21], v[16:17] op_sel_hi:[1,0]
	v_pk_mul_f32 v[12:13], v[28:29], v[16:17] op_sel_hi:[1,0]
	v_pk_mul_f32 v[14:15], v[0:1], v[16:17] op_sel_hi:[1,0]
	v_pk_mul_f32 v[0:1], v[74:75], v[16:17] op_sel_hi:[1,0]
	v_pk_mul_f32 v[2:3], v[2:3], v[16:17] op_sel_hi:[1,0]
	v_cvt_pk_bf16_f32 v16, v4, v5
	v_cvt_pk_bf16_f32 v18, v6, v7
	ds_write2_b32 v43, v16, v18 offset1:1
	v_cvt_pk_bf16_f32 v16, v8, v9
	v_cvt_pk_bf16_f32 v18, v10, v11
	ds_write2_b32 v43, v16, v18 offset0:2 offset1:3
	v_cvt_pk_bf16_f32 v16, v12, v13
	v_cvt_pk_bf16_f32 v18, v14, v15
	ds_write2_b32 v43, v16, v18 offset0:4 offset1:5
	v_cvt_pk_bf16_f32 v16, v0, v1
	v_cvt_pk_bf16_f32 v18, v2, v3
	ds_write2_b32 v43, v16, v18 offset0:6 offset1:7
	ds_write_b128 v110, v[4:7] offset:35328
	ds_write_b128 v110, v[8:11] offset:35344
	ds_write_b128 v110, v[12:15] offset:35360
	ds_write_b128 v110, v[0:3] offset:35376
	v_lshlrev_b32_e32 v16, 1, v34
	v_lshl_add_u64 v[0:1], v[46:47], 0, v[16:17]
	flat_load_dwordx4 v[12:15], v[0:1]
	flat_load_dwordx4 v[30:33], v[0:1] offset:16
	v_lshl_add_u64 v[0:1], v[48:49], 0, v[16:17]
	flat_load_dwordx4 v[8:11], v[0:1]
	flat_load_dwordx4 v[26:29], v[0:1] offset:16
	v_lshl_add_u64 v[0:1], v[50:51], 0, v[16:17]
	v_lshl_add_u64 v[18:19], v[52:53], 0, v[16:17]
	flat_load_dwordx4 v[4:7], v[0:1]
	flat_load_dwordx4 v[22:25], v[0:1] offset:16
	s_nop 0
	flat_load_dwordx4 v[0:3], v[18:19]
	s_nop 0
	flat_load_dwordx4 v[18:21], v[18:19] offset:16
	s_mov_b32 s8, 0
	s_ashr_i32 s9, s8, 31
	s_lshl_b64 s[8:9], s[8:9], 3
	s_add_u32 s8, s0, s8
	s_addc_u32 s9, s1, s9
	s_load_dwordx2 s[8:9], s[8:9], 0x90
	v_lshlrev_b32_e32 v16, 2, v34
	v_cmp_gt_u32_e32 vcc, 64, v106
	s_waitcnt lgkmcnt(0)
	s_add_u32 s8, s8, s15
	s_addc_u32 s9, s9, s14
	global_load_dwordx4 v[52:55], v16, s[8:9] offset:48
	global_load_dwordx4 v[56:59], v16, s[8:9] offset:32
	global_load_dwordx4 v[48:51], v16, s[8:9] offset:16
	global_load_dwordx4 v[34:37], v16, s[8:9]
	s_mov_b32 s8, 0
	s_ashr_i32 s9, s8, 31
	s_lshl_b64 s[8:9], s[8:9], 3
	s_add_u32 s8, s0, s8
	s_addc_u32 s9, s1, s9
	s_load_dwordx2 s[8:9], s[8:9], 0x90
	s_waitcnt lgkmcnt(0)
	s_add_u32 s8, s8, s16
	s_addc_u32 s9, s9, s17
	s_waitcnt vmcnt(0)
	v_pk_mul_f32 v[70:71], v[44:45], v[52:53] op_sel_hi:[0,1]
	v_pk_mul_f32 v[56:57], v[44:45], v[56:57] op_sel_hi:[0,1]
	v_pk_mul_f32 v[48:49], v[44:45], v[48:49] op_sel_hi:[0,1]
	v_pk_mul_f32 v[34:35], v[44:45], v[34:35] op_sel_hi:[0,1]
	v_pk_mul_f32 v[36:37], v[44:45], v[36:37] op_sel_hi:[0,1]
	v_pk_mul_f32 v[50:51], v[44:45], v[50:51] op_sel_hi:[0,1]
	v_pk_mul_f32 v[62:63], v[44:45], v[58:59] op_sel_hi:[0,1]
	v_pk_mul_f32 v[78:79], v[44:45], v[54:55] op_sel_hi:[0,1]
	global_load_dwordx4 v[66:69], v16, s[8:9] offset:48
	global_load_dwordx4 v[72:75], v16, s[8:9] offset:32
	global_load_dwordx4 v[58:61], v16, s[8:9] offset:16
	global_load_dwordx4 v[44:47], v16, s[8:9]
	s_mov_b32 s8, 0
	s_ashr_i32 s9, s8, 31
	s_lshl_b64 s[8:9], s[8:9], 3
	s_add_u32 s8, s0, s8
	s_addc_u32 s9, s1, s9
	s_load_dwordx2 s[8:9], s[8:9], 0x90
	s_waitcnt lgkmcnt(0)
	s_add_u32 s8, s8, s18
	s_addc_u32 s9, s9, s19
	s_waitcnt vmcnt(3)
	v_pk_mul_f32 v[80:81], v[42:43], v[66:67] op_sel_hi:[0,1]
	s_waitcnt vmcnt(2)
	v_pk_mul_f32 v[64:65], v[42:43], v[72:73] op_sel_hi:[0,1]
	v_pk_mul_f32 v[72:73], v[42:43], v[74:75] op_sel_hi:[0,1]
	v_pk_mul_f32 v[86:87], v[42:43], v[68:69] op_sel_hi:[0,1]
	global_load_dwordx4 v[88:91], v16, s[8:9] offset:48
	global_load_dwordx4 v[74:77], v16, s[8:9] offset:32
	global_load_dwordx4 v[66:69], v16, s[8:9] offset:16
	global_load_dwordx4 v[82:85], v16, s[8:9]
	s_mov_b32 s8, 0
	s_ashr_i32 s9, s8, 31
	s_lshl_b64 s[8:9], s[8:9], 3
	s_add_u32 s8, s0, s8
	s_addc_u32 s9, s1, s9
	s_load_dwordx2 s[8:9], s[8:9], 0x90
	s_waitcnt vmcnt(4)
	v_pk_mul_f32 v[44:45], v[42:43], v[44:45] op_sel_hi:[0,1]
	v_pk_mul_f32 v[46:47], v[42:43], v[46:47] op_sel_hi:[0,1]
	v_pk_mul_f32 v[54:55], v[42:43], v[58:59] op_sel_hi:[0,1]
	v_pk_mul_f32 v[58:59], v[42:43], v[60:61] op_sel_hi:[0,1]
	s_waitcnt lgkmcnt(0)
	s_add_u32 s8, s8, s22
	s_addc_u32 s9, s9, s23
	global_load_dwordx4 v[92:95], v16, s[8:9] offset:48
	global_load_dwordx4 v[96:99], v16, s[8:9] offset:32
	global_load_dwordx4 v[100:103], v16, s[8:9] offset:16
	global_load_dwordx4 v[112:115], v16, s[8:9]
	s_waitcnt vmcnt(7)
	v_pk_mul_f32 v[88:89], v[40:41], v[88:89] op_sel_hi:[0,1]
	s_waitcnt vmcnt(6)
	v_pk_mul_f32 v[74:75], v[40:41], v[74:75] op_sel_hi:[0,1]
	s_waitcnt vmcnt(5)
	v_pk_mul_f32 v[60:61], v[40:41], v[66:67] op_sel_hi:[0,1]
	s_waitcnt vmcnt(4)
	v_pk_mul_f32 v[42:43], v[40:41], v[82:83] op_sel_hi:[0,1]
	v_pk_mul_f32 v[52:53], v[40:41], v[84:85] op_sel_hi:[0,1]
	v_pk_mul_f32 v[66:67], v[40:41], v[68:69] op_sel_hi:[0,1]
	v_pk_mul_f32 v[82:83], v[40:41], v[76:77] op_sel_hi:[0,1]
	v_pk_mul_f32 v[40:41], v[40:41], v[90:91] op_sel_hi:[0,1]
	s_waitcnt vmcnt(3)
	v_pk_mul_f32 v[92:93], v[38:39], v[92:93] op_sel_hi:[0,1]
	s_waitcnt vmcnt(2)
	v_pk_mul_f32 v[96:97], v[38:39], v[96:97] op_sel_hi:[0,1]
	s_waitcnt vmcnt(1)
	v_pk_mul_f32 v[84:85], v[38:39], v[100:101] op_sel_hi:[0,1]
	s_waitcnt vmcnt(0)
	v_pk_mul_f32 v[68:69], v[38:39], v[112:113] op_sel_hi:[0,1]
	v_pk_mul_f32 v[76:77], v[38:39], v[114:115] op_sel_hi:[0,1]
	v_pk_mul_f32 v[90:91], v[38:39], v[102:103] op_sel_hi:[0,1]
	v_pk_mul_f32 v[98:99], v[38:39], v[98:99] op_sel_hi:[0,1]
	v_pk_mul_f32 v[38:39], v[38:39], v[94:95] op_sel_hi:[0,1]
	v_lshlrev_b32_e32 v94, 16, v33
	v_and_b32_e32 v95, 0xffff0000, v33
	v_pk_fma_f32 v[78:79], v[78:79], v[94:95], 0 op_sel_hi:[1,1,0]
	v_lshlrev_b32_e32 v94, 16, v29
	v_and_b32_e32 v95, 0xffff0000, v29
	v_pk_fma_f32 v[78:79], v[86:87], v[94:95], v[78:79]
	v_lshlrev_b32_e32 v86, 16, v25
	v_and_b32_e32 v87, 0xffff0000, v25
	v_pk_fma_f32 v[40:41], v[40:41], v[86:87], v[78:79]
	v_lshlrev_b32_e32 v78, 16, v21
	v_and_b32_e32 v79, 0xffff0000, v21
	v_pk_fma_f32 v[38:39], v[38:39], v[78:79], v[40:41]
	v_lshlrev_b32_e32 v78, 16, v32
	v_and_b32_e32 v79, 0xffff0000, v32
	v_pk_fma_f32 v[32:33], v[70:71], v[78:79], 0 op_sel_hi:[1,1,0]
	v_lshlrev_b32_e32 v70, 16, v28
	v_and_b32_e32 v71, 0xffff0000, v28
	v_pk_fma_f32 v[28:29], v[80:81], v[70:71], v[32:33]
	v_lshlrev_b32_e32 v32, 16, v24
	v_and_b32_e32 v33, 0xffff0000, v24
	v_pk_fma_f32 v[24:25], v[88:89], v[32:33], v[28:29]
	v_lshlrev_b32_e32 v28, 16, v20
	v_and_b32_e32 v29, 0xffff0000, v20
	v_pk_fma_f32 v[20:21], v[92:93], v[28:29], v[24:25]
	v_lshlrev_b32_e32 v28, 16, v31
	v_and_b32_e32 v29, 0xffff0000, v31
	v_pk_fma_f32 v[28:29], v[62:63], v[28:29], 0 op_sel_hi:[1,1,0]
	v_lshlrev_b32_e32 v62, 16, v30
	v_and_b32_e32 v63, 0xffff0000, v30
	v_pk_fma_f32 v[30:31], v[56:57], v[62:63], 0 op_sel_hi:[1,1,0]
	v_lshlrev_b32_e32 v56, 16, v26
	v_and_b32_e32 v57, 0xffff0000, v26
	v_lshlrev_b32_e32 v32, 16, v27
	v_and_b32_e32 v33, 0xffff0000, v27
	v_pk_fma_f32 v[26:27], v[64:65], v[56:57], v[30:31]
	v_lshlrev_b32_e32 v30, 16, v22
	v_and_b32_e32 v31, 0xffff0000, v22
	v_pk_fma_f32 v[28:29], v[72:73], v[32:33], v[28:29]
	v_lshlrev_b32_e32 v32, 16, v23
	v_and_b32_e32 v33, 0xffff0000, v23
	v_pk_fma_f32 v[22:23], v[74:75], v[30:31], v[26:27]
	v_lshlrev_b32_e32 v26, 16, v18
	v_and_b32_e32 v27, 0xffff0000, v18
	v_pk_fma_f32 v[28:29], v[82:83], v[32:33], v[28:29]
	v_lshlrev_b32_e32 v32, 16, v19
	v_and_b32_e32 v33, 0xffff0000, v19
	v_pk_fma_f32 v[18:19], v[96:97], v[26:27], v[22:23]
	v_lshlrev_b32_e32 v26, 16, v15
	v_and_b32_e32 v27, 0xffff0000, v15
	v_pk_fma_f32 v[26:27], v[50:51], v[26:27], 0 op_sel_hi:[1,1,0]
	v_lshlrev_b32_e32 v50, 16, v14
	v_and_b32_e32 v51, 0xffff0000, v14
	v_mul_f32_e32 v16, 0xbfb8aa3b, v39
	v_lshlrev_b32_e32 v30, 16, v11
	v_and_b32_e32 v31, 0xffff0000, v11
	v_pk_fma_f32 v[14:15], v[48:49], v[50:51], 0 op_sel_hi:[1,1,0]
	v_lshlrev_b32_e32 v48, 16, v10
	v_and_b32_e32 v49, 0xffff0000, v10
	v_exp_f32_e32 v16, v16
	v_pk_fma_f32 v[26:27], v[58:59], v[30:31], v[26:27]
	v_lshlrev_b32_e32 v30, 16, v7
	v_and_b32_e32 v31, 0xffff0000, v7
	v_pk_fma_f32 v[10:11], v[54:55], v[48:49], v[14:15]
	v_lshlrev_b32_e32 v14, 16, v6
	v_and_b32_e32 v15, 0xffff0000, v6
	v_pk_fma_f32 v[26:27], v[66:67], v[30:31], v[26:27]
	v_lshlrev_b32_e32 v30, 16, v3
	v_and_b32_e32 v31, 0xffff0000, v3
	v_pk_fma_f32 v[6:7], v[60:61], v[14:15], v[10:11]
	v_lshlrev_b32_e32 v10, 16, v2
	v_and_b32_e32 v11, 0xffff0000, v2
	v_pk_fma_f32 v[26:27], v[90:91], v[30:31], v[26:27]
	v_pk_fma_f32 v[6:7], v[84:85], v[10:11], v[6:7]
	v_mul_f32_e32 v3, 0xbfb8aa3b, v27
	v_mul_f32_e32 v2, 0xbfb8aa3b, v7
	v_add_f32_e32 v16, 1.0, v16
	v_exp_f32_e32 v3, v3
	v_exp_f32_e32 v2, v2
	v_rcp_f32_e32 v41, v16
	v_mul_f32_e32 v16, 0xbfb8aa3b, v38
	v_exp_f32_e32 v16, v16
	v_add_f32_e32 v3, 1.0, v3
	v_add_f32_e32 v2, 1.0, v2
	v_rcp_f32_e32 v31, v3
	v_mul_f32_e32 v3, 0xbfb8aa3b, v26
	v_rcp_f32_e32 v11, v2
	v_mul_f32_e32 v2, 0xbfb8aa3b, v6
	v_add_f32_e32 v16, 1.0, v16
	v_exp_f32_e32 v3, v3
	v_exp_f32_e32 v2, v2
	v_rcp_f32_e32 v40, v16
	v_mul_f32_e32 v16, 0xbfb8aa3b, v21
	v_exp_f32_e32 v16, v16
	v_add_f32_e32 v3, 1.0, v3
	v_add_f32_e32 v2, 1.0, v2
	v_rcp_f32_e32 v30, v3
	v_rcp_f32_e32 v10, v2
	v_lshlrev_b32_e32 v2, 16, v13
	v_and_b32_e32 v3, 0xffff0000, v13
	v_add_f32_e32 v16, 1.0, v16
	v_pk_fma_f32 v[2:3], v[36:37], v[2:3], 0 op_sel_hi:[1,1,0]
	v_lshlrev_b32_e32 v14, 16, v9
	v_and_b32_e32 v15, 0xffff0000, v9
	v_rcp_f32_e32 v25, v16
	v_mul_f32_e32 v16, 0xbfb8aa3b, v20
	v_pk_fma_f32 v[2:3], v[46:47], v[14:15], v[2:3]
	v_lshlrev_b32_e32 v14, 16, v5
	v_and_b32_e32 v15, 0xffff0000, v5
	v_exp_f32_e32 v16, v16
	v_pk_fma_f32 v[2:3], v[52:53], v[14:15], v[2:3]
	v_lshlrev_b32_e32 v14, 16, v1
	v_and_b32_e32 v15, 0xffff0000, v1
	v_pk_fma_f32 v[2:3], v[76:77], v[14:15], v[2:3]
	v_add_f32_e32 v16, 1.0, v16
	v_mul_f32_e32 v1, 0xbfb8aa3b, v3
	v_exp_f32_e32 v1, v1
	v_pk_fma_f32 v[28:29], v[98:99], v[32:33], v[28:29]
	v_rcp_f32_e32 v24, v16
	v_mul_f32_e32 v16, 0xbfb8aa3b, v29
	v_exp_f32_e32 v16, v16
	v_add_f32_e32 v1, 1.0, v1
	v_rcp_f32_e32 v15, v1
	v_mul_f32_e32 v1, 0xbfb8aa3b, v2
	v_exp_f32_e32 v1, v1
	v_add_f32_e32 v16, 1.0, v16
	v_lshlrev_b32_e32 v36, 16, v12
	v_and_b32_e32 v37, 0xffff0000, v12
	v_rcp_f32_e32 v33, v16
	v_mul_f32_e32 v16, 0xbfb8aa3b, v28
	v_pk_fma_f32 v[12:13], v[34:35], v[36:37], 0 op_sel_hi:[1,1,0]
	v_lshlrev_b32_e32 v34, 16, v8
	v_and_b32_e32 v35, 0xffff0000, v8
	v_exp_f32_e32 v16, v16
	v_pk_fma_f32 v[8:9], v[44:45], v[34:35], v[12:13]
	v_lshlrev_b32_e32 v12, 16, v4
	v_and_b32_e32 v13, 0xffff0000, v4
	v_add_f32_e32 v1, 1.0, v1
	v_pk_fma_f32 v[4:5], v[42:43], v[12:13], v[8:9]
	v_lshlrev_b32_e32 v8, 16, v0
	v_and_b32_e32 v9, 0xffff0000, v0
	v_rcp_f32_e32 v14, v1
	v_pk_fma_f32 v[0:1], v[68:69], v[8:9], v[4:5]
	v_add_f32_e32 v16, 1.0, v16
	v_mul_f32_e32 v4, 0xbfb8aa3b, v1
	v_exp_f32_e32 v4, v4
	v_rcp_f32_e32 v32, v16
	v_mul_f32_e32 v16, 0xbfb8aa3b, v19
	v_exp_f32_e32 v16, v16
	v_add_f32_e32 v4, 1.0, v4
	v_rcp_f32_e32 v5, v4
	v_mul_f32_e32 v4, 0xbfb8aa3b, v0
	v_add_f32_e32 v16, 1.0, v16
	v_exp_f32_e32 v4, v4
	v_rcp_f32_e32 v23, v16
	v_mul_f32_e32 v16, 0xbfb8aa3b, v18
	v_exp_f32_e32 v16, v16
	v_add_f32_e32 v4, 1.0, v4
	v_rcp_f32_e32 v4, v4
	v_pk_mul_f32 v[2:3], v[2:3], v[14:15]
	v_add_f32_e32 v16, 1.0, v16
	v_rcp_f32_e32 v22, v16
	v_pk_mul_f32 v[0:1], v[0:1], v[4:5]
	ds_write_b128 v110, v[0:3] offset:34816
	v_pk_mul_f32 v[0:1], v[6:7], v[10:11]
	v_pk_mul_f32 v[2:3], v[26:27], v[30:31]
	ds_write_b128 v110, v[0:3] offset:34832
	v_pk_mul_f32 v[0:1], v[18:19], v[22:23]
	v_pk_mul_f32 v[2:3], v[28:29], v[32:33]
	ds_write_b128 v110, v[0:3] offset:34848
	v_pk_mul_f32 v[0:1], v[20:21], v[24:25]
	v_pk_mul_f32 v[2:3], v[38:39], v[40:41]
	v_lshl_add_u32 v44, v106, 2, 0
	ds_write_b128 v110, v[0:3] offset:34864
	s_and_saveexec_b64 s[8:9], vcc
	s_cbranch_execz .LBB0_763
	v_or_b32_e32 v0, s5, v106
	v_ashrrev_i32_e32 v1, 31, v0
	v_lshlrev_b64 v[0:1], 5, v[0:1]
	v_lshl_add_u64 v[0:1], s[42:43], 0, v[0:1]
	s_lshl_b32 s52, s37, 2
	v_lshl_add_u64 v[0:1], v[0:1], 0, s[52:53]
	flat_load_dword v2, v[0:1] offset:16
	s_nop 0
	flat_load_dword v0, v[0:1]
	s_mov_b32 s38, 0
	s_ashr_i32 s39, s38, 31
	s_lshl_b64 s[38:39], s[38:39], 3
	s_add_u32 s38, s0, s38
	s_addc_u32 s39, s1, s39
	s_load_dwordx2 s[38:39], s[38:39], 0x98
	s_or_b32 s48, s37, s35
	s_ashr_i32 s49, s48, 31
	s_lshl_b64 s[48:49], s[48:49], 2
	s_mov_b32 s2, 0xbfb8aa3b
	s_waitcnt lgkmcnt(0)
	s_add_u32 s38, s38, s48
	s_addc_u32 s39, s39, s49
	global_load_dword v1, v17, s[38:39]
	s_mov_b32 s38, 0
	s_ashr_i32 s39, s38, 31
	s_lshl_b64 s[38:39], s[38:39], 3
	s_add_u32 s38, s0, s38
	s_addc_u32 s39, s1, s39
	s_load_dwordx2 s[38:39], s[38:39], 0xa0
	s_waitcnt lgkmcnt(0)
	s_add_u32 s38, s38, s48
	s_addc_u32 s39, s39, s49
	global_load_dword v3, v17, s[38:39]
	s_waitcnt vmcnt(0)
	v_mul_f32_e32 v0, 0xbfb8aa3b, v0
	v_exp_f32_e32 v0, v0
	v_mul_f32_e32 v1, 0x3fb8aa3b, v1
	v_exp_f32_e32 v1, v1
	v_add_f32_e32 v0, 1.0, v0
	v_rcp_f32_e32 v0, v0
	v_add_f32_e32 v2, v2, v3
	v_max_f32_e32 v4, 0, v2
	v_mul_f32_e64 v2, |v2|, s2
	v_exp_f32_e32 v5, v2
	s_mov_b32 s2, 0x3f2aaaab
	v_add_f32_e32 v6, 1.0, v5
	v_add_f32_e32 v2, -1.0, v6
	v_sub_f32_e32 v3, v2, v6
	v_add_f32_e32 v3, 1.0, v3
	v_sub_f32_e32 v2, v5, v2
	v_add_f32_e32 v7, v2, v3
	v_frexp_mant_f32_e32 v2, v6
	v_cmp_gt_f32_e32 vcc, s2, v2
	v_cvt_f64_f32_e32 v[2:3], v6
	v_frexp_exp_i32_f64_e32 v2, v[2:3]
	v_subbrev_co_u32_e32 v2, vcc, 0, v2, vcc
	v_sub_u32_e32 v3, 0, v2
	v_ldexp_f32 v6, v6, v3
	v_ldexp_f32 v3, v7, v3
	v_add_f32_e32 v7, -1.0, v6
	v_add_f32_e32 v8, 1.0, v7
	v_sub_f32_e32 v8, v6, v8
	v_add_f32_e32 v8, v3, v8
	v_add_f32_e32 v9, v7, v8
	v_sub_f32_e32 v7, v9, v7
	v_sub_f32_e32 v7, v8, v7
	v_add_f32_e32 v8, 1.0, v6
	v_add_f32_e32 v10, -1.0, v8
	v_sub_f32_e32 v6, v6, v10
	v_add_f32_e32 v3, v3, v6
	v_add_f32_e32 v6, v8, v3
	v_sub_f32_e32 v8, v6, v8
	v_sub_f32_e32 v3, v3, v8
	v_rcp_f32_e32 v8, v6
	v_cvt_f32_i32_e32 v2, v2
	s_mov_b32 s2, 0x3f317218
	v_mul_f32_e32 v10, v9, v8
	v_mul_f32_e32 v11, v6, v10
	v_fma_f32 v12, v10, v6, -v11
	v_fmac_f32_e32 v12, v10, v3
	v_add_f32_e32 v13, v11, v12
	v_sub_f32_e32 v14, v9, v13
	v_sub_f32_e32 v9, v9, v14
	v_sub_f32_e32 v11, v13, v11
	v_sub_f32_e32 v9, v9, v13
	v_add_f32_e32 v7, v7, v9
	v_sub_f32_e32 v9, v11, v12
	v_add_f32_e32 v7, v9, v7
	v_add_f32_e32 v9, v14, v7
	v_mul_f32_e32 v11, v8, v9
	v_mul_f32_e32 v12, v6, v11
	v_fma_f32 v6, v11, v6, -v12
	v_fmac_f32_e32 v6, v11, v3
	v_sub_f32_e32 v3, v14, v9
	v_add_f32_e32 v3, v7, v3
	v_add_f32_e32 v7, v12, v6
	v_sub_f32_e32 v13, v9, v7
	v_sub_f32_e32 v9, v9, v13
	v_sub_f32_e32 v12, v7, v12
	v_sub_f32_e32 v7, v9, v7
	v_add_f32_e32 v3, v3, v7
	v_sub_f32_e32 v6, v12, v6
	v_add_f32_e32 v3, v6, v3
	v_add_f32_e32 v6, v10, v11
	v_add_f32_e32 v3, v13, v3
	v_sub_f32_e32 v7, v6, v10
	v_mul_f32_e32 v3, v8, v3
	v_sub_f32_e32 v7, v11, v7
	v_add_f32_e32 v3, v7, v3
	v_mul_f32_e32 v10, 0x3f317218, v2
	v_add_f32_e32 v7, v6, v3
	v_fma_f32 v11, v2, s2, -v10
	v_mul_f32_e32 v8, v7, v7
	v_fmac_f32_e32 v11, 0xb102e308, v2
	v_sub_f32_e32 v2, v7, v6
	v_fmamk_f32 v9, v8, 0x3e9b6dac, v232
	v_sub_f32_e32 v2, v3, v2
	v_add_f32_e32 v3, v10, v11
	v_fmaak_f32 v9, v8, v9, 0x3f2aaada
	v_sub_f32_e32 v6, v3, v10
	v_ldexp_f32 v10, v7, 1
	v_mul_f32_e32 v7, v7, v8
	v_mul_f32_e32 v7, v7, v9
	v_add_f32_e32 v8, v10, v7
	v_sub_f32_e32 v9, v8, v10
	v_ldexp_f32 v2, v2, 1
	v_sub_f32_e32 v7, v7, v9
	v_add_f32_e32 v2, v2, v7
	v_add_f32_e32 v7, v8, v2
	v_sub_f32_e32 v8, v7, v8
	v_sub_f32_e32 v2, v2, v8
	v_add_f32_e32 v8, v3, v7
	v_sub_f32_e32 v9, v8, v3
	v_sub_f32_e32 v10, v8, v9
	v_sub_f32_e32 v6, v11, v6
	v_sub_f32_e32 v3, v3, v10
	v_sub_f32_e32 v7, v7, v9
	v_add_f32_e32 v3, v7, v3
	v_add_f32_e32 v7, v6, v2
	v_sub_f32_e32 v9, v7, v6
	v_sub_f32_e32 v10, v7, v9
	v_sub_f32_e32 v6, v6, v10
	v_sub_f32_e32 v2, v2, v9
	v_add_f32_e32 v3, v7, v3
	v_add_f32_e32 v2, v2, v6
	v_add_f32_e32 v6, v8, v3
	v_sub_f32_e32 v7, v6, v8
	v_sub_f32_e32 v3, v3, v7
	v_add_f32_e32 v2, v2, v3
	s_mov_b32 s2, 0x7f800000
	v_add_f32_e32 v2, v6, v2
	v_cmp_neq_f32_e32 vcc, s2, v5
	s_mov_b32 s2, 0x33800000
	s_nop 0
	v_cndmask_b32_e32 v2, v236, v2, vcc
	v_cmp_ngt_f32_e32 vcc, -1.0, v5
	s_nop 1
	v_cndmask_b32_e32 v2, v237, v2, vcc
	v_cmp_neq_f32_e32 vcc, -1.0, v5
	s_nop 1
	v_cndmask_b32_e32 v2, v238, v2, vcc
	v_cmp_lt_f32_e64 vcc, |v5|, s2
	s_nop 1
	v_cndmask_b32_e32 v2, v2, v5, vcc
	v_add_f32_e32 v2, v4, v2
	v_add_u32_e32 v4, -1, v234
	v_cmp_lt_i32_e32 vcc, v4, v111
	v_mul_f32_e64 v3, v2, -v1
	s_nop 0
	v_cndmask_b32_e32 v4, v4, v234, vcc
	v_lshlrev_b32_e32 v4, 2, v4
	ds_bpermute_b32 v4, v4, v3
	v_cmp_eq_u32_e32 vcc, 0, v106
	s_waitcnt lgkmcnt(0)
	v_fma_f32 v1, v2, -v1, v4
	v_add_u32_e32 v2, -2, v234
	v_cndmask_b32_e32 v1, v1, v3, vcc
	v_cmp_lt_i32_e32 vcc, v2, v111
	v_add_u32_e32 v3, 0x1cc00, v44
	s_nop 0
	v_cndmask_b32_e32 v2, v2, v234, vcc
	v_lshlrev_b32_e32 v2, 2, v2
	ds_bpermute_b32 v2, v2, v1
	v_cmp_gt_u32_e32 vcc, 2, v106
	s_waitcnt lgkmcnt(0)
	v_add_f32_e32 v2, v1, v2
	v_cndmask_b32_e32 v1, v2, v1, vcc
	v_add_u32_e32 v2, -4, v234
	v_cmp_lt_i32_e32 vcc, v2, v111
	s_nop 1
	v_cndmask_b32_e32 v2, v2, v234, vcc
	v_lshlrev_b32_e32 v2, 2, v2
	ds_bpermute_b32 v2, v2, v1
	v_cmp_gt_u32_e32 vcc, 4, v106
	s_waitcnt lgkmcnt(0)
	v_add_f32_e32 v2, v1, v2
	v_cndmask_b32_e32 v1, v2, v1, vcc
	v_add_u32_e32 v2, -8, v234
	v_cmp_lt_i32_e32 vcc, v2, v111
	s_nop 1
	v_cndmask_b32_e32 v2, v2, v234, vcc
	v_lshlrev_b32_e32 v2, 2, v2
	ds_bpermute_b32 v2, v2, v1
	v_cmp_gt_u32_e32 vcc, 8, v106
	s_waitcnt lgkmcnt(0)
	v_add_f32_e32 v2, v1, v2
	v_cndmask_b32_e32 v1, v2, v1, vcc
	v_add_u32_e32 v2, -16, v234
	v_cmp_lt_i32_e32 vcc, v2, v111
	s_nop 1
	v_cndmask_b32_e32 v2, v2, v234, vcc
	v_lshlrev_b32_e32 v2, 2, v2
	ds_bpermute_b32 v2, v2, v1
	v_cmp_gt_u32_e32 vcc, 16, v106
	s_waitcnt lgkmcnt(0)
	v_add_f32_e32 v2, v1, v2
	v_cndmask_b32_e32 v2, v2, v1, vcc
	v_subrev_u32_e32 v1, 32, v234
	v_cmp_lt_i32_e32 vcc, v1, v111
	s_nop 1
	v_cndmask_b32_e32 v1, v1, v234, vcc
	v_lshlrev_b32_e32 v1, 2, v1
	ds_bpermute_b32 v1, v1, v2
	v_cmp_gt_u32_e32 vcc, 32, v106
	s_waitcnt lgkmcnt(0)
	v_add_f32_e32 v1, v2, v1
	v_cndmask_b32_e32 v2, v1, v2, vcc
	ds_write_b32 v3, v2
	v_add_u32_e32 v2, 0x1cd00, v44
	v_cmp_eq_u32_e32 vcc, 63, v106
	ds_write_b32 v2, v0
	s_and_b64 exec, exec, vcc
	s_cbranch_execz .LBB0_763
	v_mul_f32_e32 v0, 0x3fb8aa3b, v1
	v_exp_f32_e32 v2, v0
	s_add_u32 s98, s92, s98
	s_addc_u32 s99, s93, s99
	v_mov_b64_e32 v[0:1], s[98:99]
	flat_store_dword v[0:1], v2
